# T15 loop + scalar-base (SGPR) addressing for K/V tile loads, V second chunk via immediate offset, add-with-zero removed
# speedup vs baseline: 1.0151x; 1.0123x over previous
; #define MFMA32(a, b, c) __builtin_amdgcn_mfma_f32_32x32x16_bf16((a), (b), (c), 0, 0, 0)
; #define AT_LOAD(SET, IT) { const int kl_ = AT_KB(IT); \
;     _Pragma("unroll") for (int i = 0; i < KPT; ++i) kreg[SET][i] = *(const u32x4*)(Kg + (size_t)kl_ * DQK + (tid + 256 * i) * 8); \
;     _Pragma("unroll") for (int i = 0; i < 2; ++i) vreg[SET][i] = *(const u32x4*)(Vg + (size_t)kl_ * 64 + (tid + 256 * i) * 8); \
;     __builtin_amdgcn_sched_barrier(0); }
; #define AT_WRITE(SET, BUFI) { \
;     _Pragma("unroll") for (int i = 0; i < KPT; ++i) { const int c = tid + 256 * i, row = c / KCH, kcol = c % KCH; *(u32x4*)(Ks + (BUFI) * KBUF + row * KSTR + kcol * 8) = kreg[SET][i]; } \
;     _Pragma("unroll") for (int i = 0; i < 2; ++i) { const int c = tid + 256 * i; *(u32x4*)(Vs + (BUFI) * VBUF + (c >> 3) * VSTR + (c & 7) * 8) = vreg[SET][i]; } }
; template <int DQK, bool SB, bool SMAX>
; DI void attn_item(const Params& p, char* smem, int bh, int qb, float Mb) {
;     ...
;   const int blk = (lane >> 4) & 1, tq = (lane & 15) >> 2, tp = lane & 3;
;   const int voff = (4 * h + tq) * VSTR + 16 * blk + 4 * tp;
;   AT_LOAD(0, 0)
;   AT_WRITE(0, 0)
;   AT_LOAD(0, 1)
;   __syncthreads();
;   bool stop = false;
;   for (int it2 = 0; it2 < nt && !stop; it2 += 2) {
; #pragma unroll
;    for (int st2 = 0; st2 < 2; ++st2) {
;     const int it = it2 + st2;
;     const int kb0 = AT_KB(it);
;     const bf16_t* kc = Ks + st2 * KBUF;
;     const bf16_t* vc = Vs + st2 * VBUF;
;     const bool active = kb0 < qw0 + 32;
;     f32x16 st[2];
;     if (active) {
; #pragma unroll
;       for (int kb = 0; kb < 2; ++kb)
; #pragma unroll
;         for (int i = 0; i < 16; ++i) st[kb][i] = SMAX ? negM[i] : 0.f;
; #pragma unroll
;       for (int ks = 0; ks < NKS; ++ks)
; #pragma unroll
;         for (int kb = 0; kb < 2; ++kb) {
;           const bf16x8 a = *(const bf16x8*)(kc + (kb * 32 + r) * KSTR + ks * 16 + h * 8);
;           st[kb] = MFMA32(a, qf[ks], st[kb]);
;         }
;     }
;     __builtin_amdgcn_sched_barrier(0);
;     AT_WRITE(0, st2 ^ 1)
;     AT_LOAD(0, (it + 2 < nt) ? it + 2 : nt - 1)
.LBB0_470:
	s_and_b64 vcc, exec, s[2:3]
	s_cbranch_vccz .LBB0_425
	global_load_dwordx4 v[132:135], v[186:187], off
	global_load_dwordx4 v[136:139], v[188:189], off
	global_load_dwordx4 v[140:143], v[190:191], off
	global_load_dwordx4 v[144:147], v[192:193], off
	global_load_dwordx4 v[148:151], v[194:195], off
	s_waitcnt vmcnt(9)
	ds_write_b128 v206, v[112:115]
	s_waitcnt vmcnt(8)
	ds_write_b128 v207, v[116:119]
	s_waitcnt vmcnt(7)
	ds_write_b128 v208, v[120:123]
	s_waitcnt vmcnt(6)
	ds_write_b128 v203, v[124:127] offset:26624
	s_waitcnt vmcnt(5)
	ds_write_b128 v204, v[128:131] offset:26624
	s_and_b64 vcc, exec, s[12:13]
	s_waitcnt lgkmcnt(0)
	s_barrier
	s_cbranch_vccnz .LBB0_423
	v_mov_b32_e32 v16, v177
	v_mov_b32_e32 v17, v177
	v_mov_b32_e32 v18, v177
	v_mov_b32_e32 v19, v177
	v_mov_b32_e32 v20, v177
	v_mov_b32_e32 v21, v177
	v_mov_b32_e32 v22, v177
	v_mov_b32_e32 v23, v177
	v_mov_b32_e32 v24, v177
	v_mov_b32_e32 v25, v177
	v_mov_b32_e32 v26, v177
	v_mov_b32_e32 v27, v177
	v_mov_b32_e32 v28, v177
	v_mov_b32_e32 v29, v177
	v_mov_b32_e32 v30, v177
	v_mov_b32_e32 v31, v177
	v_mov_b32_e32 v32, v177
	v_mov_b32_e32 v33, v177
	v_mov_b32_e32 v34, v177
	v_mov_b32_e32 v35, v177
	v_mov_b32_e32 v36, v177
	v_mov_b32_e32 v37, v177
	v_mov_b32_e32 v38, v177
	v_mov_b32_e32 v39, v177
	v_mov_b32_e32 v40, v177
	v_mov_b32_e32 v41, v177
	v_mov_b32_e32 v42, v177
	v_mov_b32_e32 v43, v177
	v_mov_b32_e32 v44, v177
	v_mov_b32_e32 v45, v177
	v_mov_b32_e32 v46, v177
	v_mov_b32_e32 v47, v177
	v_mov_b32_e32 v152, 0
	v_add_u32_e32 v153, v178, v202
	v_add_u32_e32 v154, v198, v200
	v_readfirstlane_b32 s20, v211
	s_add_i32 s4, s1, -1
	s_lshr_b32 s21, s16, 1
	s_mov_b32 s14, 2
	s_mul_i32 s3, s0, 0x180000
	s_add_u32 s22, s82, s3
	s_addc_u32 s23, s83, 0
	s_add_u32 s22, s22, 0x1000
	s_addc_u32 s23, s23, 0
	s_lshl_b32 s3, s0, 20
	s_add_u32 s38, s84, s3
	s_addc_u32 s39, s85, 0
	s_add_u32 s38, s38, 0x1000
	s_addc_u32 s39, s39, 0
	s_mov_b32 s26, 0xb000
	s_mov_b32 s27, 0x6800
	s_mov_b32 s28, 0x8c00
	v_add_u32_e32 v155, s26, v154
	v_add_u32_e32 v215, s28, v203
	ds_read_b128 v[216:219], v153
	ds_read_b128 v[220:223], v153 offset:6656
	ds_read_b128 v[228:231], v153 offset:32
	s_min_i32 s2, s14, s4
	s_mul_i32 s3, s2, 0x3000
	s_add_u32 s30, s22, s3
	s_addc_u32 s31, s23, 0
	s_add_u32 s34, s30, 0x1000
	s_addc_u32 s35, s31, 0
	s_lshl_b32 s3, s2, 13
	s_add_u32 s36, s38, s3
	s_addc_u32 s37, s39, 0
	global_load_dwordx4 v[112:115], v174, s[30:31] offset:-4096
	global_load_dwordx4 v[116:119], v174, s[30:31]
	global_load_dwordx4 v[120:123], v174, s[34:35]
	global_load_dwordx4 v[124:127], v174, s[36:37] offset:-4096
	global_load_dwordx4 v[128:131], v174, s[36:37]
	s_waitcnt vmcnt(9)
	ds_write_b128 v206, v[132:135] offset:13312
	s_waitcnt vmcnt(8)
	ds_write_b128 v207, v[136:139] offset:13312
	s_waitcnt vmcnt(7)
	ds_write_b128 v208, v[140:143] offset:13312
	s_waitcnt vmcnt(6)
	ds_write_b128 v215, v[144:147]
	s_waitcnt vmcnt(5)
	ds_write_b128 v215, v[148:151] offset:4608
	s_waitcnt lgkmcnt(7)
	v_mfma_f32_32x32x16_bf16 v[48:63], v[216:219], v[80:83], 0
	ds_read_b128 v[216:219], v153 offset:6688
	s_waitcnt lgkmcnt(7)
	v_mfma_f32_32x32x16_bf16 v[64:79], v[220:223], v[80:83], 0
	ds_read_b128 v[220:223], v153 offset:64
	s_waitcnt lgkmcnt(7)
	v_mfma_f32_32x32x16_bf16 v[48:63], v[228:231], v[84:87], v[48:63]
	ds_read_b128 v[228:231], v153 offset:6720
	s_waitcnt lgkmcnt(2)
	v_mfma_f32_32x32x16_bf16 v[64:79], v[216:219], v[84:87], v[64:79]
	ds_read_b128 v[216:219], v153 offset:96
	s_waitcnt lgkmcnt(2)
	v_mfma_f32_32x32x16_bf16 v[48:63], v[220:223], v[88:91], v[48:63]
	ds_read_b128 v[220:223], v153 offset:6752
	s_waitcnt lgkmcnt(2)
	v_mfma_f32_32x32x16_bf16 v[64:79], v[228:231], v[88:91], v[64:79]
	ds_read_b128 v[228:231], v153 offset:128
	s_waitcnt lgkmcnt(2)
	v_mfma_f32_32x32x16_bf16 v[48:63], v[216:219], v[92:95], v[48:63]
	ds_read_b128 v[216:219], v153 offset:6784
	s_waitcnt lgkmcnt(2)
	v_mfma_f32_32x32x16_bf16 v[64:79], v[220:223], v[92:95], v[64:79]
	ds_read_b128 v[220:223], v153 offset:160
	s_waitcnt lgkmcnt(2)
	v_mfma_f32_32x32x16_bf16 v[48:63], v[228:231], v[104:107], v[48:63]
	ds_read_b128 v[228:231], v153 offset:6816
	s_waitcnt lgkmcnt(2)
	v_mfma_f32_32x32x16_bf16 v[64:79], v[216:219], v[104:107], v[64:79]
	s_waitcnt lgkmcnt(1)
	v_mfma_f32_32x32x16_bf16 v[48:63], v[220:223], v[108:111], v[48:63]
	s_waitcnt lgkmcnt(0)
	v_mfma_f32_32x32x16_bf16 v[64:79], v[228:231], v[108:111], v[64:79]
	s_waitcnt lgkmcnt(0)
	s_barrier
	s_mov_b32 s29, s26
	s_mov_b32 s26, s27
	s_mov_b32 s27, s28
	s_mov_b32 s28, s29
	s_add_i32 s14, s14, 1
	s_cmp_eq_u32 s21, 0
	s_cbranch_scc1 .Lt15_tail
; #define MFMA32(a, b, c) __builtin_amdgcn_mfma_f32_32x32x16_bf16((a), (b), (c), 0, 0, 0)
; DI int crow(int i, int h) { return (i & 3) + 8 * (i >> 2) + 4 * h; }
; DI float fast_exp2(float x) { return __builtin_amdgcn_exp2f(x); }
; #define AT_LOAD(SET, IT) { const int kl_ = AT_KB(IT); \
;     _Pragma("unroll") for (int i = 0; i < KPT; ++i) kreg[SET][i] = *(const u32x4*)(Kg + (size_t)kl_ * DQK + (tid + 256 * i) * 8); \
;     _Pragma("unroll") for (int i = 0; i < 2; ++i) vreg[SET][i] = *(const u32x4*)(Vg + (size_t)kl_ * 64 + (tid + 256 * i) * 8); \
;     __builtin_amdgcn_sched_barrier(0); }
; #define AT_WRITE(SET, BUFI) { \
;     _Pragma("unroll") for (int i = 0; i < KPT; ++i) { const int c = tid + 256 * i, row = c / KCH, kcol = c % KCH; *(u32x4*)(Ks + (BUFI) * KBUF + row * KSTR + kcol * 8) = kreg[SET][i]; } \
;     _Pragma("unroll") for (int i = 0; i < 2; ++i) { const int c = tid + 256 * i; *(u32x4*)(Vs + (BUFI) * VBUF + (c >> 3) * VSTR + (c & 7) * 8) = vreg[SET][i]; } }
; template <int DQK, bool SB, bool SMAX>
; DI void attn_item(const Params& p, char* smem, int bh, int qb, float Mb) {
;     ...
;     if (active) {
; #pragma unroll
;       for (int kb = 0; kb < 2; ++kb)
; #pragma unroll
;         for (int i = 0; i < 16; ++i) st[kb][i] = SMAX ? negM[i] : 0.f;
; #pragma unroll
;       for (int ks = 0; ks < NKS; ++ks)
; #pragma unroll
;         for (int kb = 0; kb < 2; ++kb) {
;           const bf16x8 a = *(const bf16x8*)(kc + (kb * 32 + r) * KSTR + ks * 16 + h * 8);
;           st[kb] = MFMA32(a, qf[ks], st[kb]);
;         }
;     }
;     __builtin_amdgcn_sched_barrier(0);
;     AT_WRITE(0, st2 ^ 1)
;     AT_LOAD(0, (it + 2 < nt) ? it + 2 : nt - 1)
;     if (active) {
;       const bool diag = (kb0 + 64 > qw0);
;       bf16x8 pk[4];
;       if (!SB) {
;         if (diag) {
; #pragma unroll
;           for (int kb = 0; kb < 2; ++kb)
; #pragma unroll
;             for (int i = 0; i < 16; ++i) { const int key = kb0 + kb * 32 + crow(i, h); if (key > query) st[kb][i] = -__builtin_huge_valf(); }
;         }
;         if (SMAX) {
;           float ps = 0.f;
; #pragma unroll
;           for (int kb = 0; kb < 2; ++kb)
; #pragma unroll
;             for (int i = 0; i < 16; ++i) { const float pv = fast_exp2(st[kb][i]); st[kb][i] = pv; ps += pv; }
;           lsum += ps;
.Lt15_loop:
	v_add_u32_e32 v155, s26, v154
	v_add_u32_e32 v215, s28, v203
	ds_read_b128 v[216:219], v153 offset:13312
	ds_read_b128 v[220:223], v153 offset:19968
	ds_read_b128 v[228:231], v153 offset:13344
	ds_read_b64_tr_b16 v[236:237], v155
	ds_read_b64_tr_b16 v[238:239], v155 offset:1152
	ds_read_b64_tr_b16 v[244:245], v155 offset:64
	ds_read_b64_tr_b16 v[246:247], v155 offset:1216
	ds_read_b64_tr_b16 v[248:249], v155 offset:2304
	ds_read_b64_tr_b16 v[250:251], v155 offset:3456
	s_min_i32 s2, s14, s4
	s_mul_i32 s3, s2, 0x3000
	s_add_u32 s30, s22, s3
	s_addc_u32 s31, s23, 0
	s_add_u32 s34, s30, 0x1000
	s_addc_u32 s35, s31, 0
	s_lshl_b32 s3, s2, 13
	s_add_u32 s36, s38, s3
	s_addc_u32 s37, s39, 0
	global_load_dwordx4 v[132:135], v174, s[30:31] offset:-4096
	global_load_dwordx4 v[136:139], v174, s[30:31]
	global_load_dwordx4 v[140:143], v174, s[34:35]
	global_load_dwordx4 v[144:147], v174, s[36:37] offset:-4096
	global_load_dwordx4 v[148:151], v174, s[36:37]
	s_waitcnt vmcnt(9)
	ds_write_b128 v206, v[112:115]
	s_waitcnt vmcnt(8)
	ds_write_b128 v207, v[116:119]
	s_waitcnt vmcnt(7)
	ds_write_b128 v208, v[120:123]
	s_waitcnt vmcnt(6)
	ds_write_b128 v215, v[124:127]
	s_waitcnt vmcnt(5)
	ds_write_b128 v215, v[128:131] offset:4608
	v_exp_f32_e32 v48, v48
	v_exp_f32_e32 v49, v49
	v_exp_f32_e32 v50, v50
	v_exp_f32_e32 v51, v51
	s_waitcnt lgkmcnt(13)
	v_mfma_f32_32x32x16_bf16 v[0:15], v[216:219], v[80:83], 0
	ds_read_b128 v[216:219], v153 offset:20000
	v_exp_f32_e32 v52, v52
	v_add_f32_e32 v224, v49, v48
	v_cvt_pk_bf16_f32 v188, v48, v49
	v_exp_f32_e32 v53, v53
	s_waitcnt lgkmcnt(13)
	v_mfma_f32_32x32x16_bf16 v[156:171], v[220:223], v[80:83], 0
	ds_read_b128 v[220:223], v153 offset:13376
	v_add_f32_e32 v224, v50, v224
	v_exp_f32_e32 v54, v54
	v_add_f32_e32 v224, v51, v224
	v_cvt_pk_bf16_f32 v189, v50, v51
	s_waitcnt lgkmcnt(13)
	v_mfma_f32_32x32x16_bf16 v[0:15], v[228:231], v[84:87], v[0:15]
	ds_read_b128 v[228:231], v153 offset:20032
	v_exp_f32_e32 v55, v55
	v_add_f32_e32 v224, v52, v224
	v_exp_f32_e32 v56, v56
	v_add_f32_e32 v224, v53, v224
	s_waitcnt lgkmcnt(2)
	v_mfma_f32_32x32x16_bf16 v[156:171], v[216:219], v[84:87], v[156:171]
	ds_read_b128 v[216:219], v153 offset:13408
	v_cvt_pk_bf16_f32 v190, v52, v53
	v_exp_f32_e32 v57, v57
	v_add_f32_e32 v224, v54, v224
	v_exp_f32_e32 v58, v58
	s_waitcnt lgkmcnt(2)
	v_mfma_f32_32x32x16_bf16 v[0:15], v[220:223], v[88:91], v[0:15]
	ds_read_b128 v[220:223], v153 offset:20064
	v_add_f32_e32 v224, v55, v224
	v_cvt_pk_bf16_f32 v191, v54, v55
	v_exp_f32_e32 v59, v59
	v_add_f32_e32 v224, v56, v224
	s_nop 0
	v_mfma_f32_32x32x16_bf16 v[32:47], v[236:239], v[188:191], v[32:47]
	ds_read_b64_tr_b16 v[236:237], v155 offset:2368
	ds_read_b64_tr_b16 v[238:239], v155 offset:3520
	v_exp_f32_e32 v60, v60
	v_add_f32_e32 v224, v57, v224
	v_cvt_pk_bf16_f32 v192, v56, v57
	v_exp_f32_e32 v61, v61
	v_mfma_f32_32x32x16_bf16 v[16:31], v[244:247], v[188:191], v[16:31]
	ds_read_b64_tr_b16 v[244:245], v155 offset:4608
	ds_read_b64_tr_b16 v[246:247], v155 offset:5760
	v_add_f32_e32 v224, v58, v224
	v_exp_f32_e32 v62, v62
	v_add_f32_e32 v224, v59, v224
	v_cvt_pk_bf16_f32 v193, v58, v59
	s_waitcnt lgkmcnt(6)
	v_mfma_f32_32x32x16_bf16 v[156:171], v[228:231], v[88:91], v[156:171]
	ds_read_b128 v[228:231], v153 offset:13440
	v_exp_f32_e32 v63, v63
	v_add_f32_e32 v224, v60, v224
	v_add_f32_e32 v224, v61, v224
	v_add_f32_e32 v224, v62, v224
	s_waitcnt lgkmcnt(6)
	v_mfma_f32_32x32x16_bf16 v[0:15], v[216:219], v[92:95], v[0:15]
	ds_read_b128 v[216:219], v153 offset:20096
	v_add_f32_e32 v224, v63, v224
	v_cvt_pk_bf16_f32 v194, v60, v61
	v_cvt_pk_bf16_f32 v195, v62, v63
	v_exp_f32_e32 v64, v64
	s_waitcnt lgkmcnt(6)
	v_mfma_f32_32x32x16_bf16 v[156:171], v[220:223], v[92:95], v[156:171]
	ds_read_b128 v[220:223], v153 offset:13472
	v_exp_f32_e32 v65, v65
	v_exp_f32_e32 v66, v66
	v_exp_f32_e32 v67, v67
	v_add_f32_e32 v224, v64, v224
	v_mfma_f32_32x32x16_bf16 v[32:47], v[248:251], v[192:195], v[32:47]
	ds_read_b64_tr_b16 v[248:249], v155 offset:4672
	ds_read_b64_tr_b16 v[250:251], v155 offset:5824
	v_exp_f32_e32 v68, v68
	v_add_f32_e32 v224, v65, v224
	v_cvt_pk_bf16_f32 v188, v64, v65
	v_exp_f32_e32 v69, v69
	s_waitcnt lgkmcnt(7)
	v_mfma_f32_32x32x16_bf16 v[16:31], v[236:239], v[192:195], v[16:31]
	ds_read_b64_tr_b16 v[236:237], v155 offset:6912
	ds_read_b64_tr_b16 v[238:239], v155 offset:8064
	v_add_f32_e32 v224, v66, v224
	v_exp_f32_e32 v70, v70
	v_add_f32_e32 v224, v67, v224
	v_cvt_pk_bf16_f32 v189, v66, v67
	s_waitcnt lgkmcnt(6)
	v_mfma_f32_32x32x16_bf16 v[0:15], v[228:231], v[104:107], v[0:15]
	ds_read_b128 v[228:231], v153 offset:20128
	v_exp_f32_e32 v71, v71
	v_add_f32_e32 v224, v68, v224
	v_exp_f32_e32 v72, v72
	v_add_f32_e32 v224, v69, v224
	s_waitcnt lgkmcnt(6)
	v_mfma_f32_32x32x16_bf16 v[156:171], v[216:219], v[104:107], v[156:171]
	v_cvt_pk_bf16_f32 v190, v68, v69
	v_exp_f32_e32 v73, v73
	v_add_f32_e32 v224, v70, v224
	v_exp_f32_e32 v74, v74
	s_waitcnt lgkmcnt(5)
	v_mfma_f32_32x32x16_bf16 v[0:15], v[220:223], v[108:111], v[0:15]
	v_add_f32_e32 v224, v71, v224
	v_cvt_pk_bf16_f32 v191, v70, v71
	v_exp_f32_e32 v75, v75
	v_add_f32_e32 v224, v72, v224
	s_nop 0
	v_mfma_f32_32x32x16_bf16 v[32:47], v[244:247], v[188:191], v[32:47]
	ds_read_b64_tr_b16 v[244:245], v155 offset:6976
	ds_read_b64_tr_b16 v[246:247], v155 offset:8128
	v_exp_f32_e32 v76, v76
	v_add_f32_e32 v224, v73, v224
	v_cvt_pk_bf16_f32 v192, v72, v73
	v_exp_f32_e32 v77, v77
	s_waitcnt lgkmcnt(5)
	v_mfma_f32_32x32x16_bf16 v[16:31], v[248:251], v[188:191], v[16:31]
	v_add_f32_e32 v224, v74, v224
	v_exp_f32_e32 v78, v78
	v_add_f32_e32 v224, v75, v224
	v_cvt_pk_bf16_f32 v193, v74, v75
	s_waitcnt lgkmcnt(2)
	v_mfma_f32_32x32x16_bf16 v[156:171], v[228:231], v[108:111], v[156:171]
	v_exp_f32_e32 v79, v79
	v_add_f32_e32 v224, v76, v224
	v_add_f32_e32 v224, v77, v224
	v_add_f32_e32 v224, v78, v224
	v_add_f32_e32 v224, v79, v224
	v_cvt_pk_bf16_f32 v194, v76, v77
	v_cvt_pk_bf16_f32 v195, v78, v79
	s_nop 1
	v_mfma_f32_32x32x16_bf16 v[32:47], v[236:239], v[192:195], v[32:47]
	s_waitcnt lgkmcnt(0)
	v_mfma_f32_32x32x16_bf16 v[16:31], v[244:247], v[192:195], v[16:31]
	v_add_f32_e32 v152, v152, v224
	s_waitcnt lgkmcnt(0)
	s_barrier
; #define MFMA32(a, b, c) __builtin_amdgcn_mfma_f32_32x32x16_bf16((a), (b), (c), 0, 0, 0)
; DI int crow(int i, int h) { return (i & 3) + 8 * (i >> 2) + 4 * h; }
; DI float fast_exp2(float x) { return __builtin_amdgcn_exp2f(x); }
; #define AT_LOAD(SET, IT) { const int kl_ = AT_KB(IT); \
;     _Pragma("unroll") for (int i = 0; i < KPT; ++i) kreg[SET][i] = *(const u32x4*)(Kg + (size_t)kl_ * DQK + (tid + 256 * i) * 8); \
;     _Pragma("unroll") for (int i = 0; i < 2; ++i) vreg[SET][i] = *(const u32x4*)(Vg + (size_t)kl_ * 64 + (tid + 256 * i) * 8); \
;     __builtin_amdgcn_sched_barrier(0); }
; #define AT_WRITE(SET, BUFI) { \
;     _Pragma("unroll") for (int i = 0; i < KPT; ++i) { const int c = tid + 256 * i, row = c / KCH, kcol = c % KCH; *(u32x4*)(Ks + (BUFI) * KBUF + row * KSTR + kcol * 8) = kreg[SET][i]; } \
;     _Pragma("unroll") for (int i = 0; i < 2; ++i) { const int c = tid + 256 * i; *(u32x4*)(Vs + (BUFI) * VBUF + (c >> 3) * VSTR + (c & 7) * 8) = vreg[SET][i]; } }
; template <int DQK, bool SB, bool SMAX>
; DI void attn_item(const Params& p, char* smem, int bh, int qb, float Mb) {
;     ...
;     if (active) {
; #pragma unroll
;       for (int kb = 0; kb < 2; ++kb)
; #pragma unroll
;         for (int i = 0; i < 16; ++i) st[kb][i] = SMAX ? negM[i] : 0.f;
; #pragma unroll
;       for (int ks = 0; ks < NKS; ++ks)
; #pragma unroll
;         for (int kb = 0; kb < 2; ++kb) {
;           const bf16x8 a = *(const bf16x8*)(kc + (kb * 32 + r) * KSTR + ks * 16 + h * 8);
;           st[kb] = MFMA32(a, qf[ks], st[kb]);
;         }
;     }
;     __builtin_amdgcn_sched_barrier(0);
;     AT_WRITE(0, st2 ^ 1)
;     AT_LOAD(0, (it + 2 < nt) ? it + 2 : nt - 1)
;     if (active) {
;       const bool diag = (kb0 + 64 > qw0);
;       bf16x8 pk[4];
;       if (!SB) {
;         if (diag) {
; #pragma unroll
;           for (int kb = 0; kb < 2; ++kb)
; #pragma unroll
;             for (int i = 0; i < 16; ++i) { const int key = kb0 + kb * 32 + crow(i, h); if (key > query) st[kb][i] = -__builtin_huge_valf(); }
;         }
;         if (SMAX) {
;           float ps = 0.f;
; #pragma unroll
;           for (int kb = 0; kb < 2; ++kb)
; #pragma unroll
;             for (int i = 0; i < 16; ++i) { const float pv = fast_exp2(st[kb][i]); st[kb][i] = pv; ps += pv; }
;           lsum += ps;
	s_mov_b32 s29, s26
	s_mov_b32 s26, s27
	s_mov_b32 s27, s28
	s_mov_b32 s28, s29
	s_add_i32 s14, s14, 1
	v_add_u32_e32 v155, s26, v154
	v_add_u32_e32 v215, s28, v203
	ds_read_b128 v[216:219], v153
	ds_read_b128 v[220:223], v153 offset:6656
	ds_read_b128 v[228:231], v153 offset:32
	ds_read_b64_tr_b16 v[236:237], v155
	ds_read_b64_tr_b16 v[238:239], v155 offset:1152
	ds_read_b64_tr_b16 v[244:245], v155 offset:64
	ds_read_b64_tr_b16 v[246:247], v155 offset:1216
	ds_read_b64_tr_b16 v[248:249], v155 offset:2304
	ds_read_b64_tr_b16 v[250:251], v155 offset:3456
	s_min_i32 s2, s14, s4
	s_mul_i32 s3, s2, 0x3000
	s_add_u32 s30, s22, s3
	s_addc_u32 s31, s23, 0
	s_add_u32 s34, s30, 0x1000
	s_addc_u32 s35, s31, 0
	s_lshl_b32 s3, s2, 13
	s_add_u32 s36, s38, s3
	s_addc_u32 s37, s39, 0
	global_load_dwordx4 v[112:115], v174, s[30:31] offset:-4096
	global_load_dwordx4 v[116:119], v174, s[30:31]
	global_load_dwordx4 v[120:123], v174, s[34:35]
	global_load_dwordx4 v[124:127], v174, s[36:37] offset:-4096
	global_load_dwordx4 v[128:131], v174, s[36:37]
	s_waitcnt vmcnt(9)
	ds_write_b128 v206, v[132:135] offset:13312
	s_waitcnt vmcnt(8)
	ds_write_b128 v207, v[136:139] offset:13312
	s_waitcnt vmcnt(7)
	ds_write_b128 v208, v[140:143] offset:13312
	s_waitcnt vmcnt(6)
	ds_write_b128 v215, v[144:147]
	s_waitcnt vmcnt(5)
	ds_write_b128 v215, v[148:151] offset:4608
	v_exp_f32_e32 v0, v0
	v_exp_f32_e32 v1, v1
	v_exp_f32_e32 v2, v2
	v_exp_f32_e32 v3, v3
	s_waitcnt lgkmcnt(13)
	v_mfma_f32_32x32x16_bf16 v[48:63], v[216:219], v[80:83], 0
	ds_read_b128 v[216:219], v153 offset:6688
	v_exp_f32_e32 v4, v4
	v_add_f32_e32 v224, v1, v0
	v_cvt_pk_bf16_f32 v188, v0, v1
	v_exp_f32_e32 v5, v5
	s_waitcnt lgkmcnt(13)
	v_mfma_f32_32x32x16_bf16 v[64:79], v[220:223], v[80:83], 0
	ds_read_b128 v[220:223], v153 offset:64
	v_add_f32_e32 v224, v2, v224
	v_exp_f32_e32 v6, v6
	v_add_f32_e32 v224, v3, v224
	v_cvt_pk_bf16_f32 v189, v2, v3
	s_waitcnt lgkmcnt(13)
	v_mfma_f32_32x32x16_bf16 v[48:63], v[228:231], v[84:87], v[48:63]
	ds_read_b128 v[228:231], v153 offset:6720
	v_exp_f32_e32 v7, v7
	v_add_f32_e32 v224, v4, v224
	v_exp_f32_e32 v8, v8
	v_add_f32_e32 v224, v5, v224
	s_waitcnt lgkmcnt(2)
	v_mfma_f32_32x32x16_bf16 v[64:79], v[216:219], v[84:87], v[64:79]
	ds_read_b128 v[216:219], v153 offset:96
	v_cvt_pk_bf16_f32 v190, v4, v5
	v_exp_f32_e32 v9, v9
	v_add_f32_e32 v224, v6, v224
	v_exp_f32_e32 v10, v10
	s_waitcnt lgkmcnt(2)
	v_mfma_f32_32x32x16_bf16 v[48:63], v[220:223], v[88:91], v[48:63]
	ds_read_b128 v[220:223], v153 offset:6752
	v_add_f32_e32 v224, v7, v224
	v_cvt_pk_bf16_f32 v191, v6, v7
	v_exp_f32_e32 v11, v11
	v_add_f32_e32 v224, v8, v224
	s_nop 0
	v_mfma_f32_32x32x16_bf16 v[32:47], v[236:239], v[188:191], v[32:47]
	ds_read_b64_tr_b16 v[236:237], v155 offset:2368
	ds_read_b64_tr_b16 v[238:239], v155 offset:3520
	v_exp_f32_e32 v12, v12
	v_add_f32_e32 v224, v9, v224
	v_cvt_pk_bf16_f32 v192, v8, v9
	v_exp_f32_e32 v13, v13
	v_mfma_f32_32x32x16_bf16 v[16:31], v[244:247], v[188:191], v[16:31]
	ds_read_b64_tr_b16 v[244:245], v155 offset:4608
	ds_read_b64_tr_b16 v[246:247], v155 offset:5760
	v_add_f32_e32 v224, v10, v224
	v_exp_f32_e32 v14, v14
	v_add_f32_e32 v224, v11, v224
	v_cvt_pk_bf16_f32 v193, v10, v11
	s_waitcnt lgkmcnt(6)
	v_mfma_f32_32x32x16_bf16 v[64:79], v[228:231], v[88:91], v[64:79]
	ds_read_b128 v[228:231], v153 offset:128
	v_exp_f32_e32 v15, v15
	v_add_f32_e32 v224, v12, v224
	v_add_f32_e32 v224, v13, v224
	v_add_f32_e32 v224, v14, v224
	s_waitcnt lgkmcnt(6)
	v_mfma_f32_32x32x16_bf16 v[48:63], v[216:219], v[92:95], v[48:63]
	ds_read_b128 v[216:219], v153 offset:6784
	v_add_f32_e32 v224, v15, v224
	v_cvt_pk_bf16_f32 v194, v12, v13
	v_cvt_pk_bf16_f32 v195, v14, v15
	v_exp_f32_e32 v156, v156
	s_waitcnt lgkmcnt(6)
	v_mfma_f32_32x32x16_bf16 v[64:79], v[220:223], v[92:95], v[64:79]
	ds_read_b128 v[220:223], v153 offset:160
	v_exp_f32_e32 v157, v157
	v_exp_f32_e32 v158, v158
	v_exp_f32_e32 v159, v159
	v_add_f32_e32 v224, v156, v224
	v_mfma_f32_32x32x16_bf16 v[32:47], v[248:251], v[192:195], v[32:47]
	ds_read_b64_tr_b16 v[248:249], v155 offset:4672
	ds_read_b64_tr_b16 v[250:251], v155 offset:5824
	v_exp_f32_e32 v160, v160
	v_add_f32_e32 v224, v157, v224
	v_cvt_pk_bf16_f32 v188, v156, v157
	v_exp_f32_e32 v161, v161
	s_waitcnt lgkmcnt(7)
	v_mfma_f32_32x32x16_bf16 v[16:31], v[236:239], v[192:195], v[16:31]
	ds_read_b64_tr_b16 v[236:237], v155 offset:6912
	ds_read_b64_tr_b16 v[238:239], v155 offset:8064
	v_add_f32_e32 v224, v158, v224
	v_exp_f32_e32 v162, v162
	v_add_f32_e32 v224, v159, v224
	v_cvt_pk_bf16_f32 v189, v158, v159
	s_waitcnt lgkmcnt(6)
	v_mfma_f32_32x32x16_bf16 v[48:63], v[228:231], v[104:107], v[48:63]
	ds_read_b128 v[228:231], v153 offset:6816
	v_exp_f32_e32 v163, v163
	v_add_f32_e32 v224, v160, v224
	v_exp_f32_e32 v164, v164
	v_add_f32_e32 v224, v161, v224
	s_waitcnt lgkmcnt(6)
	v_mfma_f32_32x32x16_bf16 v[64:79], v[216:219], v[104:107], v[64:79]
	v_cvt_pk_bf16_f32 v190, v160, v161
	v_exp_f32_e32 v165, v165
	v_add_f32_e32 v224, v162, v224
	v_exp_f32_e32 v166, v166
	s_waitcnt lgkmcnt(5)
	v_mfma_f32_32x32x16_bf16 v[48:63], v[220:223], v[108:111], v[48:63]
	v_add_f32_e32 v224, v163, v224
	v_cvt_pk_bf16_f32 v191, v162, v163
	v_exp_f32_e32 v167, v167
	v_add_f32_e32 v224, v164, v224
	s_nop 0
	v_mfma_f32_32x32x16_bf16 v[32:47], v[244:247], v[188:191], v[32:47]
	ds_read_b64_tr_b16 v[244:245], v155 offset:6976
	ds_read_b64_tr_b16 v[246:247], v155 offset:8128
	v_exp_f32_e32 v168, v168
	v_add_f32_e32 v224, v165, v224
	v_cvt_pk_bf16_f32 v192, v164, v165
	v_exp_f32_e32 v169, v169
	s_waitcnt lgkmcnt(5)
	v_mfma_f32_32x32x16_bf16 v[16:31], v[248:251], v[188:191], v[16:31]
	v_add_f32_e32 v224, v166, v224
	v_exp_f32_e32 v170, v170
	v_add_f32_e32 v224, v167, v224
	v_cvt_pk_bf16_f32 v193, v166, v167
	s_waitcnt lgkmcnt(2)
	v_mfma_f32_32x32x16_bf16 v[64:79], v[228:231], v[108:111], v[64:79]
	v_exp_f32_e32 v171, v171
	v_add_f32_e32 v224, v168, v224
	v_add_f32_e32 v224, v169, v224
	v_add_f32_e32 v224, v170, v224
	v_add_f32_e32 v224, v171, v224
	v_cvt_pk_bf16_f32 v194, v168, v169
	v_cvt_pk_bf16_f32 v195, v170, v171
	s_nop 1
	v_mfma_f32_32x32x16_bf16 v[32:47], v[236:239], v[192:195], v[32:47]
	s_waitcnt lgkmcnt(0)
	v_mfma_f32_32x32x16_bf16 v[16:31], v[244:247], v[192:195], v[16:31]
	v_add_f32_e32 v152, v152, v224
	s_waitcnt lgkmcnt(0)
	s_barrier
	s_mov_b32 s29, s26
	s_mov_b32 s26, s27
	s_mov_b32 s27, s28
	s_mov_b32 s28, s29
	s_add_i32 s14, s14, 1
	s_add_i32 s21, s21, -1
	s_cmp_lg_u32 s21, 0
	s_cbranch_scc1 .Lt15_loop
; #define MFMA32(a, b, c) __builtin_amdgcn_mfma_f32_32x32x16_bf16((a), (b), (c), 0, 0, 0)
; DI int crow(int i, int h) { return (i & 3) + 8 * (i >> 2) + 4 * h; }
; #define AT_LOAD(SET, IT) { const int kl_ = AT_KB(IT); \
;     _Pragma("unroll") for (int i = 0; i < KPT; ++i) kreg[SET][i] = *(const u32x4*)(Kg + (size_t)kl_ * DQK + (tid + 256 * i) * 8); \
;     _Pragma("unroll") for (int i = 0; i < 2; ++i) vreg[SET][i] = *(const u32x4*)(Vg + (size_t)kl_ * 64 + (tid + 256 * i) * 8); \
;     __builtin_amdgcn_sched_barrier(0); }
; template <int DQK, bool SB, bool SMAX>
; DI void attn_item(const Params& p, char* smem, int bh, int qb, float Mb) {
;     ...
;   const int blk = (lane >> 4) & 1, tq = (lane & 15) >> 2, tp = lane & 3;
;   const int voff = (4 * h + tq) * VSTR + 16 * blk + 4 * tp;
;   AT_LOAD(0, 0)
;   AT_WRITE(0, 0)
;   AT_LOAD(0, 1)
;   __syncthreads();
;   bool stop = false;
;   for (int it2 = 0; it2 < nt && !stop; it2 += 2) {
; #pragma unroll
;    for (int st2 = 0; st2 < 2; ++st2) {
;     const int it = it2 + st2;
;     const int kb0 = AT_KB(it);
;     const bf16_t* kc = Ks + st2 * KBUF;
;     const bf16_t* vc = Vs + st2 * VBUF;
;     const bool active = kb0 < qw0 + 32;
;     f32x16 st[2];
;     if (active) {
; #pragma unroll
;       for (int kb = 0; kb < 2; ++kb)
; #pragma unroll
;         for (int i = 0; i < 16; ++i) st[kb][i] = SMAX ? negM[i] : 0.f;
; #pragma unroll
;       for (int ks = 0; ks < NKS; ++ks)
; #pragma unroll
;         for (int kb = 0; kb < 2; ++kb) {
;           const bf16x8 a = *(const bf16x8*)(kc + (kb * 32 + r) * KSTR + ks * 16 + h * 8);
;           st[kb] = MFMA32(a, qf[ks], st[kb]);
;         }
;     }
;     __builtin_amdgcn_sched_barrier(0);
;     AT_WRITE(0, st2 ^ 1)
;     AT_LOAD(0, (it + 2 < nt) ? it + 2 : nt - 1)
;     if (active) {
;       const bool diag = (kb0 + 64 > qw0);
;       bf16x8 pk[4];
;       if (!SB) {
;         if (diag) {
; #pragma unroll
;           for (int kb = 0; kb < 2; ++kb)
; #pragma unroll
;             for (int i = 0; i < 16; ++i) { const int key = kb0 + kb * 32 + crow(i, h); if (key > query) st[kb][i] = -__builtin_huge_valf(); }
.Lt15_tail:
	v_add_u32_e32 v155, s26, v154
	v_add_u32_e32 v215, s28, v203
	ds_read_b128 v[216:219], v153 offset:13312
	ds_read_b128 v[220:223], v153 offset:19968
	ds_read_b128 v[228:231], v153 offset:13344
	s_min_i32 s2, s14, s4
	s_mul_i32 s3, s2, 0x3000
	s_add_u32 s30, s22, s3
	s_addc_u32 s31, s23, 0
	s_add_u32 s34, s30, 0x1000
	s_addc_u32 s35, s31, 0
	s_lshl_b32 s3, s2, 13
	s_add_u32 s36, s38, s3
	s_addc_u32 s37, s39, 0
	global_load_dwordx4 v[132:135], v174, s[30:31] offset:-4096
	global_load_dwordx4 v[136:139], v174, s[30:31]
	global_load_dwordx4 v[140:143], v174, s[34:35]
	global_load_dwordx4 v[144:147], v174, s[36:37] offset:-4096
	global_load_dwordx4 v[148:151], v174, s[36:37]
	s_waitcnt vmcnt(9)
	ds_write_b128 v206, v[112:115]
	s_waitcnt vmcnt(8)
	ds_write_b128 v207, v[116:119]
	s_waitcnt vmcnt(7)
	ds_write_b128 v208, v[120:123]
	s_waitcnt vmcnt(6)
	ds_write_b128 v215, v[124:127]
	s_waitcnt vmcnt(5)
	ds_write_b128 v215, v[128:131] offset:4608
	s_waitcnt lgkmcnt(7)
	v_mfma_f32_32x32x16_bf16 v[0:15], v[216:219], v[80:83], 0
	ds_read_b128 v[216:219], v153 offset:20000
	s_waitcnt lgkmcnt(7)
	v_mfma_f32_32x32x16_bf16 v[156:171], v[220:223], v[80:83], 0
	ds_read_b128 v[220:223], v153 offset:13376
	s_waitcnt lgkmcnt(7)
	v_mfma_f32_32x32x16_bf16 v[0:15], v[228:231], v[84:87], v[0:15]
	ds_read_b128 v[228:231], v153 offset:20032
	s_waitcnt lgkmcnt(2)
	v_mfma_f32_32x32x16_bf16 v[156:171], v[216:219], v[84:87], v[156:171]
	ds_read_b128 v[216:219], v153 offset:13408
	s_waitcnt lgkmcnt(2)
	v_mfma_f32_32x32x16_bf16 v[0:15], v[220:223], v[88:91], v[0:15]
	ds_read_b128 v[220:223], v153 offset:20064
	s_waitcnt lgkmcnt(2)
	v_mfma_f32_32x32x16_bf16 v[156:171], v[228:231], v[88:91], v[156:171]
	ds_read_b128 v[228:231], v153 offset:13440
	s_waitcnt lgkmcnt(2)
	v_mfma_f32_32x32x16_bf16 v[0:15], v[216:219], v[92:95], v[0:15]
	ds_read_b128 v[216:219], v153 offset:20096
	s_waitcnt lgkmcnt(2)
	v_mfma_f32_32x32x16_bf16 v[156:171], v[220:223], v[92:95], v[156:171]
	ds_read_b128 v[220:223], v153 offset:13472
	s_waitcnt lgkmcnt(2)
	v_mfma_f32_32x32x16_bf16 v[0:15], v[228:231], v[104:107], v[0:15]
	ds_read_b128 v[228:231], v153 offset:20128
	s_waitcnt lgkmcnt(2)
	v_mfma_f32_32x32x16_bf16 v[156:171], v[216:219], v[104:107], v[156:171]
	s_waitcnt lgkmcnt(1)
	v_mfma_f32_32x32x16_bf16 v[0:15], v[220:223], v[108:111], v[0:15]
	s_waitcnt lgkmcnt(0)
	v_mfma_f32_32x32x16_bf16 v[156:171], v[228:231], v[108:111], v[156:171]
	s_lshl_b32 s2, s1, 6
	s_add_i32 s2, s2, 0xffffff80
	s_nop 7
	s_nop 3
	v_add_u32_e32 v227, s2, v197
	v_add_u32_e32 v225, 0, v227
	v_cmp_le_u32_e32 vcc, v225, v176
	s_nop 1
	v_cndmask_b32_e32 v48, v210, v48, vcc
	v_add_u32_e32 v225, 1, v227
	v_cmp_le_u32_e32 vcc, v225, v176
	s_nop 1
	v_cndmask_b32_e32 v49, v210, v49, vcc
	v_add_u32_e32 v225, 2, v227
	v_cmp_le_u32_e32 vcc, v225, v176
	s_nop 1
	v_cndmask_b32_e32 v50, v210, v50, vcc
	v_add_u32_e32 v225, 3, v227
	v_cmp_le_u32_e32 vcc, v225, v176
	s_nop 1
	v_cndmask_b32_e32 v51, v210, v51, vcc
	v_add_u32_e32 v225, 8, v227
	v_cmp_le_u32_e32 vcc, v225, v176
	s_nop 1
	v_cndmask_b32_e32 v52, v210, v52, vcc
	v_add_u32_e32 v225, 9, v227
	v_cmp_le_u32_e32 vcc, v225, v176
	s_nop 1
	v_cndmask_b32_e32 v53, v210, v53, vcc
	v_add_u32_e32 v225, 10, v227
	v_cmp_le_u32_e32 vcc, v225, v176
	s_nop 1
	v_cndmask_b32_e32 v54, v210, v54, vcc
	v_add_u32_e32 v225, 11, v227
	v_cmp_le_u32_e32 vcc, v225, v176
	s_nop 1
	v_cndmask_b32_e32 v55, v210, v55, vcc
	v_add_u32_e32 v225, 16, v227
	v_cmp_le_u32_e32 vcc, v225, v176
	s_nop 1
	v_cndmask_b32_e32 v56, v210, v56, vcc
	v_add_u32_e32 v225, 17, v227
	v_cmp_le_u32_e32 vcc, v225, v176
	s_nop 1
	v_cndmask_b32_e32 v57, v210, v57, vcc
	v_add_u32_e32 v225, 18, v227
	v_cmp_le_u32_e32 vcc, v225, v176
	s_nop 1
	v_cndmask_b32_e32 v58, v210, v58, vcc
	v_add_u32_e32 v225, 19, v227
	v_cmp_le_u32_e32 vcc, v225, v176
	s_nop 1
	v_cndmask_b32_e32 v59, v210, v59, vcc
	v_add_u32_e32 v225, 24, v227
	v_cmp_le_u32_e32 vcc, v225, v176
	s_nop 1
	v_cndmask_b32_e32 v60, v210, v60, vcc
	v_add_u32_e32 v225, 25, v227
	v_cmp_le_u32_e32 vcc, v225, v176
	s_nop 1
	v_cndmask_b32_e32 v61, v210, v61, vcc
	v_add_u32_e32 v225, 26, v227
	v_cmp_le_u32_e32 vcc, v225, v176
	s_nop 1
	v_cndmask_b32_e32 v62, v210, v62, vcc
	v_add_u32_e32 v225, 27, v227
	v_cmp_le_u32_e32 vcc, v225, v176
	s_nop 1
	v_cndmask_b32_e32 v63, v210, v63, vcc
	v_add_u32_e32 v225, 32, v227
	v_cmp_le_u32_e32 vcc, v225, v176
	s_nop 1
	v_cndmask_b32_e32 v64, v210, v64, vcc
	v_add_u32_e32 v225, 33, v227
	v_cmp_le_u32_e32 vcc, v225, v176
	s_nop 1
	v_cndmask_b32_e32 v65, v210, v65, vcc
	v_add_u32_e32 v225, 34, v227
	v_cmp_le_u32_e32 vcc, v225, v176
	s_nop 1
	v_cndmask_b32_e32 v66, v210, v66, vcc
	v_add_u32_e32 v225, 35, v227
	v_cmp_le_u32_e32 vcc, v225, v176
	s_nop 1
	v_cndmask_b32_e32 v67, v210, v67, vcc
	v_add_u32_e32 v225, 40, v227
	v_cmp_le_u32_e32 vcc, v225, v176
	s_nop 1
	v_cndmask_b32_e32 v68, v210, v68, vcc
	v_add_u32_e32 v225, 41, v227
	v_cmp_le_u32_e32 vcc, v225, v176
	s_nop 1
	v_cndmask_b32_e32 v69, v210, v69, vcc
	v_add_u32_e32 v225, 42, v227
	v_cmp_le_u32_e32 vcc, v225, v176
	s_nop 1
	v_cndmask_b32_e32 v70, v210, v70, vcc
	v_add_u32_e32 v225, 43, v227
	v_cmp_le_u32_e32 vcc, v225, v176
	s_nop 1
	v_cndmask_b32_e32 v71, v210, v71, vcc
	v_add_u32_e32 v225, 48, v227
	v_cmp_le_u32_e32 vcc, v225, v176
	s_nop 1
	v_cndmask_b32_e32 v72, v210, v72, vcc
	v_add_u32_e32 v225, 49, v227
	v_cmp_le_u32_e32 vcc, v225, v176
	s_nop 1
	v_cndmask_b32_e32 v73, v210, v73, vcc
	v_add_u32_e32 v225, 50, v227
	v_cmp_le_u32_e32 vcc, v225, v176
	s_nop 1
	v_cndmask_b32_e32 v74, v210, v74, vcc
	v_add_u32_e32 v225, 51, v227
	v_cmp_le_u32_e32 vcc, v225, v176
	s_nop 1
; #define MFMA32(a, b, c) __builtin_amdgcn_mfma_f32_32x32x16_bf16((a), (b), (c), 0, 0, 0)
; DI unsigned pk_bf16(float lo, float hi) { f32x2 v = {lo, hi}; bf2_t b = __builtin_convertvector(v, bf2_t); return __builtin_bit_cast(unsigned, b); }
; DI int crow(int i, int h) { return (i & 3) + 8 * (i >> 2) + 4 * h; }
; DI float fast_exp2(float x) { return __builtin_amdgcn_exp2f(x); }
; template <int DQK, bool SB, bool SMAX>
; DI void attn_item(const Params& p, char* smem, int bh, int qb, float Mb) {
;     ...
;             for (int i = 0; i < 16; ++i) { const int key = kb0 + kb * 32 + crow(i, h); if (key > query) st[kb][i] = -__builtin_huge_valf(); }
;         }
;         if (SMAX) {
;           float ps = 0.f;
; #pragma unroll
;           for (int kb = 0; kb < 2; ++kb)
; #pragma unroll
;             for (int i = 0; i < 16; ++i) { const float pv = fast_exp2(st[kb][i]); st[kb][i] = pv; ps += pv; }
;           lsum += ps;
;     ...
; #pragma unroll
;       for (int kb = 0; kb < 2; ++kb)
; #pragma unroll
;         for (int s = 0; s < 2; ++s) {
;           u32x4 w;
; #pragma unroll
;           for (int e = 0; e < 4; ++e) w[e] = pk_bf16(st[kb][8 * s + 2 * e], st[kb][8 * s + 2 * e + 1]);
;           pk[kb * 2 + s] = __builtin_bit_cast(bf16x8, w);
;         }
; #pragma unroll
;       for (int kk = 0; kk < 4; ++kk)
; #pragma unroll
;         for (int db = 0; db < 2; ++db) {
;           const s16x4 v0 = __builtin_amdgcn_ds_read_tr16_b64_v4i16((lds_s16x4*)(vc + voff + (16 * kk) * VSTR + 32 * db));
;           const s16x4 v1 = __builtin_amdgcn_ds_read_tr16_b64_v4i16((lds_s16x4*)(vc + voff + (16 * kk + 8) * VSTR + 32 * db));
;           const bf16x8 vf = __builtin_shufflevector(v0, v1, 0, 1, 2, 3, 4, 5, 6, 7);
;           O[db] = MFMA32(vf, pk[kk], O[db]);
;         }
	v_cndmask_b32_e32 v75, v210, v75, vcc
	v_add_u32_e32 v225, 56, v227
	v_cmp_le_u32_e32 vcc, v225, v176
	s_nop 1
	v_cndmask_b32_e32 v76, v210, v76, vcc
	v_add_u32_e32 v225, 57, v227
	v_cmp_le_u32_e32 vcc, v225, v176
	s_nop 1
	v_cndmask_b32_e32 v77, v210, v77, vcc
	v_add_u32_e32 v225, 58, v227
	v_cmp_le_u32_e32 vcc, v225, v176
	s_nop 1
	v_cndmask_b32_e32 v78, v210, v78, vcc
	v_add_u32_e32 v225, 59, v227
	v_cmp_le_u32_e32 vcc, v225, v176
	s_nop 1
	v_cndmask_b32_e32 v79, v210, v79, vcc
	ds_read_b64_tr_b16 v[236:237], v155
	ds_read_b64_tr_b16 v[238:239], v155 offset:1152
	ds_read_b64_tr_b16 v[244:245], v155 offset:64
	ds_read_b64_tr_b16 v[246:247], v155 offset:1216
	ds_read_b64_tr_b16 v[248:249], v155 offset:2304
	ds_read_b64_tr_b16 v[250:251], v155 offset:3456
	v_exp_f32_e32 v48, v48
	v_exp_f32_e32 v49, v49
	v_exp_f32_e32 v50, v50
	v_exp_f32_e32 v51, v51
	v_exp_f32_e32 v52, v52
	v_add_f32_e32 v224, v49, v48
	v_cvt_pk_bf16_f32 v188, v48, v49
	v_exp_f32_e32 v53, v53
	v_add_f32_e32 v224, v50, v224
	v_exp_f32_e32 v54, v54
	v_add_f32_e32 v224, v51, v224
	v_cvt_pk_bf16_f32 v189, v50, v51
	v_exp_f32_e32 v55, v55
	v_add_f32_e32 v224, v52, v224
	v_exp_f32_e32 v56, v56
	v_add_f32_e32 v224, v53, v224
	v_cvt_pk_bf16_f32 v190, v52, v53
	v_exp_f32_e32 v57, v57
	v_add_f32_e32 v224, v54, v224
	v_exp_f32_e32 v58, v58
	v_add_f32_e32 v224, v55, v224
	v_cvt_pk_bf16_f32 v191, v54, v55
	v_exp_f32_e32 v59, v59
	v_add_f32_e32 v224, v56, v224
	v_exp_f32_e32 v60, v60
	v_add_f32_e32 v224, v57, v224
	v_cvt_pk_bf16_f32 v192, v56, v57
	v_exp_f32_e32 v61, v61
	v_add_f32_e32 v224, v58, v224
	v_exp_f32_e32 v62, v62
	v_add_f32_e32 v224, v59, v224
	v_cvt_pk_bf16_f32 v193, v58, v59
	v_exp_f32_e32 v63, v63
	v_add_f32_e32 v224, v60, v224
	v_add_f32_e32 v224, v61, v224
	v_add_f32_e32 v224, v62, v224
	v_add_f32_e32 v224, v63, v224
	v_cvt_pk_bf16_f32 v194, v60, v61
	v_cvt_pk_bf16_f32 v195, v62, v63
	s_nop 1
	s_waitcnt lgkmcnt(4)
	v_mfma_f32_32x32x16_bf16 v[32:47], v[236:239], v[188:191], v[32:47]
	ds_read_b64_tr_b16 v[236:237], v155 offset:2368
	ds_read_b64_tr_b16 v[238:239], v155 offset:3520
	s_waitcnt lgkmcnt(4)
	v_mfma_f32_32x32x16_bf16 v[16:31], v[244:247], v[188:191], v[16:31]
	ds_read_b64_tr_b16 v[244:245], v155 offset:4608
	ds_read_b64_tr_b16 v[246:247], v155 offset:5760
	s_waitcnt lgkmcnt(4)
	v_mfma_f32_32x32x16_bf16 v[32:47], v[248:251], v[192:195], v[32:47]
	ds_read_b64_tr_b16 v[248:249], v155 offset:4672
	ds_read_b64_tr_b16 v[250:251], v155 offset:5824
	s_waitcnt lgkmcnt(4)
	v_mfma_f32_32x32x16_bf16 v[16:31], v[236:239], v[192:195], v[16:31]
	ds_read_b64_tr_b16 v[236:237], v155 offset:6912
	ds_read_b64_tr_b16 v[238:239], v155 offset:8064
	v_exp_f32_e32 v64, v64
	v_exp_f32_e32 v65, v65
	v_exp_f32_e32 v66, v66
	v_exp_f32_e32 v67, v67
	v_add_f32_e32 v224, v64, v224
	v_exp_f32_e32 v68, v68
	v_add_f32_e32 v224, v65, v224
	v_cvt_pk_bf16_f32 v188, v64, v65
	v_exp_f32_e32 v69, v69
	v_add_f32_e32 v224, v66, v224
	v_exp_f32_e32 v70, v70
	v_add_f32_e32 v224, v67, v224
	v_cvt_pk_bf16_f32 v189, v66, v67
	v_exp_f32_e32 v71, v71
	v_add_f32_e32 v224, v68, v224
	v_exp_f32_e32 v72, v72
	v_add_f32_e32 v224, v69, v224
	v_cvt_pk_bf16_f32 v190, v68, v69
	v_exp_f32_e32 v73, v73
	v_add_f32_e32 v224, v70, v224
	v_exp_f32_e32 v74, v74
	v_add_f32_e32 v224, v71, v224
	v_cvt_pk_bf16_f32 v191, v70, v71
	v_exp_f32_e32 v75, v75
	v_add_f32_e32 v224, v72, v224
	v_exp_f32_e32 v76, v76
	v_add_f32_e32 v224, v73, v224
	v_cvt_pk_bf16_f32 v192, v72, v73
	v_exp_f32_e32 v77, v77
	v_add_f32_e32 v224, v74, v224
	v_exp_f32_e32 v78, v78
	v_add_f32_e32 v224, v75, v224
	v_cvt_pk_bf16_f32 v193, v74, v75
	v_exp_f32_e32 v79, v79
	v_add_f32_e32 v224, v76, v224
	v_add_f32_e32 v224, v77, v224
	v_add_f32_e32 v224, v78, v224
	v_add_f32_e32 v224, v79, v224
	v_cvt_pk_bf16_f32 v194, v76, v77
	v_cvt_pk_bf16_f32 v195, v78, v79
	s_nop 1
	s_waitcnt lgkmcnt(4)
	v_mfma_f32_32x32x16_bf16 v[32:47], v[244:247], v[188:191], v[32:47]
	ds_read_b64_tr_b16 v[244:245], v155 offset:6976
	ds_read_b64_tr_b16 v[246:247], v155 offset:8128
	s_waitcnt lgkmcnt(4)
	v_mfma_f32_32x32x16_bf16 v[16:31], v[248:251], v[188:191], v[16:31]
	s_waitcnt lgkmcnt(2)
	v_mfma_f32_32x32x16_bf16 v[32:47], v[236:239], v[192:195], v[32:47]
	s_waitcnt lgkmcnt(0)
	v_mfma_f32_32x32x16_bf16 v[16:31], v[244:247], v[192:195], v[16:31]
	v_add_f32_e32 v152, v152, v224
	s_waitcnt lgkmcnt(0)
	s_barrier
	s_mov_b32 s29, s26
	s_mov_b32 s26, s27
	s_mov_b32 s27, s28
	s_mov_b32 s28, s29
	s_add_i32 s14, s14, 1
	s_lshl_b32 s2, s4, 6
	s_cmp_gt_u32 s2, s20
	s_cbranch_scc1 .Lt15_done
; DI int crow(int i, int h) { return (i & 3) + 8 * (i >> 2) + 4 * h; }
; DI float fast_exp2(float x) { return __builtin_amdgcn_exp2f(x); }
; template <int DQK, bool SB, bool SMAX>
; DI void attn_item(const Params& p, char* smem, int bh, int qb, float Mb) {
;     ...
;         if (diag) {
; #pragma unroll
;           for (int kb = 0; kb < 2; ++kb)
; #pragma unroll
;             for (int i = 0; i < 16; ++i) { const int key = kb0 + kb * 32 + crow(i, h); if (key > query) st[kb][i] = -__builtin_huge_valf(); }
;         }
;         if (SMAX) {
;           float ps = 0.f;
; #pragma unroll
;           for (int kb = 0; kb < 2; ++kb)
; #pragma unroll
;             for (int i = 0; i < 16; ++i) { const float pv = fast_exp2(st[kb][i]); st[kb][i] = pv; ps += pv; }
;           lsum += ps;
	v_add_u32_e32 v155, s26, v154
	v_add_u32_e32 v227, s2, v197
	v_add_u32_e32 v225, 0, v227
	v_cmp_le_u32_e32 vcc, v225, v176
	s_nop 1
	v_cndmask_b32_e32 v0, v210, v0, vcc
	v_add_u32_e32 v225, 1, v227
	v_cmp_le_u32_e32 vcc, v225, v176
	s_nop 1
	v_cndmask_b32_e32 v1, v210, v1, vcc
	v_add_u32_e32 v225, 2, v227
	v_cmp_le_u32_e32 vcc, v225, v176
	s_nop 1
	v_cndmask_b32_e32 v2, v210, v2, vcc
	v_add_u32_e32 v225, 3, v227
	v_cmp_le_u32_e32 vcc, v225, v176
	s_nop 1
	v_cndmask_b32_e32 v3, v210, v3, vcc
	v_add_u32_e32 v225, 8, v227
	v_cmp_le_u32_e32 vcc, v225, v176
	s_nop 1
	v_cndmask_b32_e32 v4, v210, v4, vcc
	v_add_u32_e32 v225, 9, v227
	v_cmp_le_u32_e32 vcc, v225, v176
	s_nop 1
	v_cndmask_b32_e32 v5, v210, v5, vcc
	v_add_u32_e32 v225, 10, v227
	v_cmp_le_u32_e32 vcc, v225, v176
	s_nop 1
	v_cndmask_b32_e32 v6, v210, v6, vcc
	v_add_u32_e32 v225, 11, v227
	v_cmp_le_u32_e32 vcc, v225, v176
	s_nop 1
	v_cndmask_b32_e32 v7, v210, v7, vcc
	v_add_u32_e32 v225, 16, v227
	v_cmp_le_u32_e32 vcc, v225, v176
	s_nop 1
	v_cndmask_b32_e32 v8, v210, v8, vcc
	v_add_u32_e32 v225, 17, v227
	v_cmp_le_u32_e32 vcc, v225, v176
	s_nop 1
	v_cndmask_b32_e32 v9, v210, v9, vcc
	v_add_u32_e32 v225, 18, v227
	v_cmp_le_u32_e32 vcc, v225, v176
	s_nop 1
	v_cndmask_b32_e32 v10, v210, v10, vcc
	v_add_u32_e32 v225, 19, v227
	v_cmp_le_u32_e32 vcc, v225, v176
	s_nop 1
	v_cndmask_b32_e32 v11, v210, v11, vcc
	v_add_u32_e32 v225, 24, v227
	v_cmp_le_u32_e32 vcc, v225, v176
	s_nop 1
	v_cndmask_b32_e32 v12, v210, v12, vcc
	v_add_u32_e32 v225, 25, v227
	v_cmp_le_u32_e32 vcc, v225, v176
	s_nop 1
	v_cndmask_b32_e32 v13, v210, v13, vcc
	v_add_u32_e32 v225, 26, v227
	v_cmp_le_u32_e32 vcc, v225, v176
	s_nop 1
	v_cndmask_b32_e32 v14, v210, v14, vcc
	v_add_u32_e32 v225, 27, v227
	v_cmp_le_u32_e32 vcc, v225, v176
	s_nop 1
	v_cndmask_b32_e32 v15, v210, v15, vcc
	v_add_u32_e32 v225, 32, v227
	v_cmp_le_u32_e32 vcc, v225, v176
	s_nop 1
	v_cndmask_b32_e32 v156, v210, v156, vcc
	v_add_u32_e32 v225, 33, v227
	v_cmp_le_u32_e32 vcc, v225, v176
	s_nop 1
	v_cndmask_b32_e32 v157, v210, v157, vcc
	v_add_u32_e32 v225, 34, v227
	v_cmp_le_u32_e32 vcc, v225, v176
	s_nop 1
	v_cndmask_b32_e32 v158, v210, v158, vcc
	v_add_u32_e32 v225, 35, v227
	v_cmp_le_u32_e32 vcc, v225, v176
	s_nop 1
	v_cndmask_b32_e32 v159, v210, v159, vcc
	v_add_u32_e32 v225, 40, v227
	v_cmp_le_u32_e32 vcc, v225, v176
	s_nop 1
	v_cndmask_b32_e32 v160, v210, v160, vcc
	v_add_u32_e32 v225, 41, v227
	v_cmp_le_u32_e32 vcc, v225, v176
	s_nop 1
	v_cndmask_b32_e32 v161, v210, v161, vcc
	v_add_u32_e32 v225, 42, v227
	v_cmp_le_u32_e32 vcc, v225, v176
	s_nop 1
	v_cndmask_b32_e32 v162, v210, v162, vcc
	v_add_u32_e32 v225, 43, v227
	v_cmp_le_u32_e32 vcc, v225, v176
	s_nop 1
	v_cndmask_b32_e32 v163, v210, v163, vcc
	v_add_u32_e32 v225, 48, v227
	v_cmp_le_u32_e32 vcc, v225, v176
	s_nop 1
	v_cndmask_b32_e32 v164, v210, v164, vcc
	v_add_u32_e32 v225, 49, v227
	v_cmp_le_u32_e32 vcc, v225, v176
	s_nop 1
	v_cndmask_b32_e32 v165, v210, v165, vcc
	v_add_u32_e32 v225, 50, v227
	v_cmp_le_u32_e32 vcc, v225, v176
	s_nop 1
	v_cndmask_b32_e32 v166, v210, v166, vcc
	v_add_u32_e32 v225, 51, v227
	v_cmp_le_u32_e32 vcc, v225, v176
	s_nop 1
	v_cndmask_b32_e32 v167, v210, v167, vcc
	v_add_u32_e32 v225, 56, v227
	v_cmp_le_u32_e32 vcc, v225, v176
	s_nop 1
	v_cndmask_b32_e32 v168, v210, v168, vcc
	v_add_u32_e32 v225, 57, v227
	v_cmp_le_u32_e32 vcc, v225, v176
	s_nop 1
	v_cndmask_b32_e32 v169, v210, v169, vcc
	v_add_u32_e32 v225, 58, v227
	v_cmp_le_u32_e32 vcc, v225, v176
	s_nop 1
	v_cndmask_b32_e32 v170, v210, v170, vcc
	v_add_u32_e32 v225, 59, v227
	v_cmp_le_u32_e32 vcc, v225, v176
	s_nop 1
	v_cndmask_b32_e32 v171, v210, v171, vcc
	ds_read_b64_tr_b16 v[236:237], v155
	ds_read_b64_tr_b16 v[238:239], v155 offset:1152
	ds_read_b64_tr_b16 v[244:245], v155 offset:64
	ds_read_b64_tr_b16 v[246:247], v155 offset:1216
	ds_read_b64_tr_b16 v[248:249], v155 offset:2304
	ds_read_b64_tr_b16 v[250:251], v155 offset:3456
	v_exp_f32_e32 v0, v0
	v_exp_f32_e32 v1, v1
	v_exp_f32_e32 v2, v2
	v_exp_f32_e32 v3, v3
	v_exp_f32_e32 v4, v4
	v_add_f32_e32 v224, v1, v0
	v_cvt_pk_bf16_f32 v188, v0, v1
	v_exp_f32_e32 v5, v5
	v_add_f32_e32 v224, v2, v224
	v_exp_f32_e32 v6, v6
	v_add_f32_e32 v224, v3, v224
	v_cvt_pk_bf16_f32 v189, v2, v3
	v_exp_f32_e32 v7, v7
	v_add_f32_e32 v224, v4, v224
	v_exp_f32_e32 v8, v8
	v_add_f32_e32 v224, v5, v224
	v_cvt_pk_bf16_f32 v190, v4, v5
	v_exp_f32_e32 v9, v9
	v_add_f32_e32 v224, v6, v224
	v_exp_f32_e32 v10, v10
	v_add_f32_e32 v224, v7, v224
	v_cvt_pk_bf16_f32 v191, v6, v7
	v_exp_f32_e32 v11, v11
	v_add_f32_e32 v224, v8, v224
	v_exp_f32_e32 v12, v12
	v_add_f32_e32 v224, v9, v224
	v_cvt_pk_bf16_f32 v192, v8, v9
	v_exp_f32_e32 v13, v13
	v_add_f32_e32 v224, v10, v224
	v_exp_f32_e32 v14, v14
	v_add_f32_e32 v224, v11, v224
	v_cvt_pk_bf16_f32 v193, v10, v11
	v_exp_f32_e32 v15, v15
	v_add_f32_e32 v224, v12, v224
	v_add_f32_e32 v224, v13, v224
	v_add_f32_e32 v224, v14, v224
	v_add_f32_e32 v224, v15, v224
	v_cvt_pk_bf16_f32 v194, v12, v13
	v_cvt_pk_bf16_f32 v195, v14, v15
	s_nop 1
	s_waitcnt lgkmcnt(4)
; #define MFMA32(a, b, c) __builtin_amdgcn_mfma_f32_32x32x16_bf16((a), (b), (c), 0, 0, 0)
; DI unsigned pk_bf16(float lo, float hi) { f32x2 v = {lo, hi}; bf2_t b = __builtin_convertvector(v, bf2_t); return __builtin_bit_cast(unsigned, b); }
; template <int DQK, bool SB, bool SMAX>
; DI void attn_item(const Params& p, char* smem, int bh, int qb, float Mb) {
;     ...
; #pragma unroll
;       for (int kb = 0; kb < 2; ++kb)
; #pragma unroll
;         for (int s = 0; s < 2; ++s) {
;           u32x4 w;
; #pragma unroll
;           for (int e = 0; e < 4; ++e) w[e] = pk_bf16(st[kb][8 * s + 2 * e], st[kb][8 * s + 2 * e + 1]);
;           pk[kb * 2 + s] = __builtin_bit_cast(bf16x8, w);
;         }
; #pragma unroll
;       for (int kk = 0; kk < 4; ++kk)
; #pragma unroll
;         for (int db = 0; db < 2; ++db) {
;           const s16x4 v0 = __builtin_amdgcn_ds_read_tr16_b64_v4i16((lds_s16x4*)(vc + voff + (16 * kk) * VSTR + 32 * db));
;           const s16x4 v1 = __builtin_amdgcn_ds_read_tr16_b64_v4i16((lds_s16x4*)(vc + voff + (16 * kk + 8) * VSTR + 32 * db));
;           const bf16x8 vf = __builtin_shufflevector(v0, v1, 0, 1, 2, 3, 4, 5, 6, 7);
;           O[db] = MFMA32(vf, pk[kk], O[db]);
;         }
	v_mfma_f32_32x32x16_bf16 v[32:47], v[236:239], v[188:191], v[32:47]
	ds_read_b64_tr_b16 v[236:237], v155 offset:2368
	ds_read_b64_tr_b16 v[238:239], v155 offset:3520
	s_waitcnt lgkmcnt(4)
	v_mfma_f32_32x32x16_bf16 v[16:31], v[244:247], v[188:191], v[16:31]
	ds_read_b64_tr_b16 v[244:245], v155 offset:4608
	ds_read_b64_tr_b16 v[246:247], v155 offset:5760
	s_waitcnt lgkmcnt(4)
	v_mfma_f32_32x32x16_bf16 v[32:47], v[248:251], v[192:195], v[32:47]
	ds_read_b64_tr_b16 v[248:249], v155 offset:4672
	ds_read_b64_tr_b16 v[250:251], v155 offset:5824
	s_waitcnt lgkmcnt(4)
	v_mfma_f32_32x32x16_bf16 v[16:31], v[236:239], v[192:195], v[16:31]
	ds_read_b64_tr_b16 v[236:237], v155 offset:6912
	ds_read_b64_tr_b16 v[238:239], v155 offset:8064
	v_exp_f32_e32 v156, v156
	v_exp_f32_e32 v157, v157
	v_exp_f32_e32 v158, v158
	v_exp_f32_e32 v159, v159
	v_add_f32_e32 v224, v156, v224
	v_exp_f32_e32 v160, v160
	v_add_f32_e32 v224, v157, v224
	v_cvt_pk_bf16_f32 v188, v156, v157
	v_exp_f32_e32 v161, v161
	v_add_f32_e32 v224, v158, v224
	v_exp_f32_e32 v162, v162
	v_add_f32_e32 v224, v159, v224
	v_cvt_pk_bf16_f32 v189, v158, v159
	v_exp_f32_e32 v163, v163
	v_add_f32_e32 v224, v160, v224
	v_exp_f32_e32 v164, v164
	v_add_f32_e32 v224, v161, v224
	v_cvt_pk_bf16_f32 v190, v160, v161
	v_exp_f32_e32 v165, v165
	v_add_f32_e32 v224, v162, v224
	v_exp_f32_e32 v166, v166
	v_add_f32_e32 v224, v163, v224
	v_cvt_pk_bf16_f32 v191, v162, v163
	v_exp_f32_e32 v167, v167
	v_add_f32_e32 v224, v164, v224
	v_exp_f32_e32 v168, v168
	v_add_f32_e32 v224, v165, v224
	v_cvt_pk_bf16_f32 v192, v164, v165
	v_exp_f32_e32 v169, v169
	v_add_f32_e32 v224, v166, v224
	v_exp_f32_e32 v170, v170
	v_add_f32_e32 v224, v167, v224
	v_cvt_pk_bf16_f32 v193, v166, v167
	v_exp_f32_e32 v171, v171
	v_add_f32_e32 v224, v168, v224
	v_add_f32_e32 v224, v169, v224
	v_add_f32_e32 v224, v170, v224
	v_add_f32_e32 v224, v171, v224
	v_cvt_pk_bf16_f32 v194, v168, v169
	v_cvt_pk_bf16_f32 v195, v170, v171
	s_nop 1
	s_waitcnt lgkmcnt(4)
	v_mfma_f32_32x32x16_bf16 v[32:47], v[244:247], v[188:191], v[32:47]
	ds_read_b64_tr_b16 v[244:245], v155 offset:6976
	ds_read_b64_tr_b16 v[246:247], v155 offset:8128
	s_waitcnt lgkmcnt(4)
	v_mfma_f32_32x32x16_bf16 v[16:31], v[248:251], v[188:191], v[16:31]
	s_waitcnt lgkmcnt(2)
	v_mfma_f32_32x32x16_bf16 v[32:47], v[236:239], v[192:195], v[32:47]
	s_waitcnt lgkmcnt(0)
	v_mfma_f32_32x32x16_bf16 v[16:31], v[244:247], v[192:195], v[16:31]
	v_add_f32_e32 v152, v152, v224
	s_waitcnt lgkmcnt(0)
